# v9 + GEMM tail-round tiles (in-proj, out-proj, down) spread across XCDs (one WG per XCD-balanced CU)
# speedup vs baseline: 1.0891x; 1.0151x over previous
; template <int EPI>
; __device__ __forceinline__ void gemm_tile(const bf16_t* __restrict__ A, const int lda, const bf16_t* __restrict__ Bt, const int ldb,
;                                           const int K, const int m0, const int n0, void* Cout, const int ldc, char* lds, const int tid) {
;     ...
;   for (int kt = 0; kt < nt; ++kt) {
;     asm volatile("s_waitcnt vmcnt(0)" ::: "memory");
;     __syncthreads();
;     if (kt + 1 < nt) stageB(kt + 1, (kt + 1) & 1);
;     const char* sa = lds + (kt & 1) * 32768;
;     const char* sb = sa + 16384;
;     bf16x8 af[2][4], bfr[2][4];
; #pragma unroll
;     for (int ks = 0; ks < 2; ++ks) {
; #pragma unroll
;       for (int m = 0; m < 4; ++m) af[ks][m] = *(const bf16x8*)(sa + (wr * 64 + m * 16 + fr) * 128 + (ks ? xk1 : xk0));
; #pragma unroll
;       for (int n = 0; n < 4; ++n) bfr[ks][n] = *(const bf16x8*)(sb + (wc * 64 + n * 16 + fr) * 128 + (ks ? xk1 : xk0));
;     }
;     if (kt + 1 < nt) stageA(kt + 1, (kt + 1) & 1);
; #pragma unroll
;     for (int ks = 0; ks < 2; ++ks)
; #pragma unroll
;       for (int m = 0; m < 4; ++m)
; #pragma unroll
;         for (int n = 0; n < 4; ++n) acc[m][n] = __builtin_amdgcn_mfma_f32_16x16x32_bf16(bfr[ks][n], af[ks][m], acc[m][n], 0, 0, 0);
;   }
; template <int EPI>
; __device__ __forceinline__ void gemm_phase(const bf16_t* A, int lda, const bf16_t* Bt, int ldb, int K, int ntn, void* C, int ldc, char* lds, int bid, int nb, const int tid) {
;     ...
;   for (int L = pos; L < ntiles; L += nb) {
;     int mt, nn;
;     if (EPI == EPI_SWIGLU) { mt = L / ntn; nn = L % ntn; }
;     else { const int gid = L / nig, fm = gid * GM, gsz = min(nM - fm, GM), rem = L - gid * nig; mt = fm + rem % gsz; nn = rem / gsz; }
.LBB0_104:
	s_add_i32 s25, s26, 0x8000
	s_and_b32 s23, s25, 0x8000
	v_add_u32_e32 v139, s23, v176
	v_add_u32_e32 v70, 0x4000, v139
	v_lshl_add_u64 v[68:69], v[140:141], 0, s[34:35]
	v_readfirstlane_b32 s27, v70
	v_add_u32_e32 v70, 0x5000, v139
	s_mov_b32 m0, s27
	v_readfirstlane_b32 s27, v70
	v_add_u32_e32 v70, 0x6000, v139
	s_waitcnt vmcnt(0)
	s_waitcnt vmcnt(0) lgkmcnt(0)
	s_barrier
	global_load_lds_dwordx4 v[68:69], off
	v_lshl_add_u64 v[68:69], v[142:143], 0, s[34:35]
	s_mov_b32 m0, s27
	v_readfirstlane_b32 s27, v70
	v_add_u32_e32 v70, 0x7000, v139
	global_load_lds_dwordx4 v[68:69], off
	v_lshl_add_u64 v[68:69], v[144:145], 0, s[34:35]
	s_mov_b32 m0, s27
	v_readfirstlane_b32 s27, v70
	global_load_lds_dwordx4 v[68:69], off
	v_lshl_add_u64 v[68:69], v[146:147], 0, s[34:35]
	s_mov_b32 m0, s27
	s_and_b32 s26, s26, 0x8000
	global_load_lds_dwordx4 v[68:69], off
	v_or_b32_e32 v68, s26, v174
	v_add_u32_e32 v69, v68, v181
	v_add_u32_e32 v68, v68, v180
	v_or_b32_e32 v72, s26, v175
	v_readfirstlane_b32 s26, v139
	v_add_u32_e32 v168, 0x1000, v139
	ds_read_b128 v[104:107], v69
	ds_read_b128 v[100:103], v69 offset:2048
	ds_read_b128 v[96:99], v69 offset:4096
	ds_read_b128 v[84:87], v69 offset:6144
	ds_read_b128 v[190:193], v68 offset:16384
	ds_read_b128 v[194:197], v68 offset:18432
	ds_read_b128 v[198:201], v68 offset:20480
	ds_read_b128 v[202:205], v68 offset:22528
	v_add_u32_e32 v68, v72, v181
	v_add_u32_e32 v76, v72, v180
	v_lshl_add_u64 v[158:159], v[148:149], 0, s[34:35]
	s_mov_b32 m0, s26
	v_readfirstlane_b32 s26, v168
	v_add_u32_e32 v168, 0x2000, v139
	ds_read_b128 v[206:209], v68
	ds_read_b128 v[210:213], v68 offset:2048
	ds_read_b128 v[92:95], v68 offset:4096
	ds_read_b128 v[68:71], v68 offset:6144
	ds_read_b128 v[88:91], v76 offset:16384
	ds_read_b128 v[80:83], v76 offset:18432
	ds_read_b128 v[72:75], v76 offset:20480
	ds_read_b128 v[76:79], v76 offset:22528
	global_load_lds_dwordx4 v[158:159], off
	v_lshl_add_u64 v[158:159], v[150:151], 0, s[34:35]
	s_mov_b32 m0, s26
	v_readfirstlane_b32 s26, v168
	v_add_u32_e32 v139, 0x3000, v139
	global_load_lds_dwordx4 v[158:159], off
	v_lshl_add_u64 v[158:159], v[152:153], 0, s[34:35]
	s_mov_b32 m0, s26
	v_readfirstlane_b32 s26, v139
	global_load_lds_dwordx4 v[158:159], off
	v_lshl_add_u64 v[158:159], v[154:155], 0, s[34:35]
	s_mov_b32 m0, s26
	s_waitcnt lgkmcnt(0)
	v_mfma_f32_16x16x32_bf16 v[64:67], v[190:193], v[104:107], v[64:67]
	global_load_lds_dwordx4 v[158:159], off
	s_add_u32 s34, s34, 0x80
	v_mfma_f32_16x16x32_bf16 v[60:63], v[194:197], v[104:107], v[60:63]
	s_addc_u32 s35, s35, 0
	s_cmpk_eq_i32 s34, 0x1580
	s_mov_b32 s26, s25
	v_mfma_f32_16x16x32_bf16 v[56:59], v[198:201], v[104:107], v[56:59]
	v_mfma_f32_16x16x32_bf16 v[52:55], v[202:205], v[104:107], v[52:55]
	v_mfma_f32_16x16x32_bf16 v[36:39], v[190:193], v[100:103], v[36:39]
	v_mfma_f32_16x16x32_bf16 v[28:31], v[194:197], v[100:103], v[28:31]
	v_mfma_f32_16x16x32_bf16 v[20:23], v[198:201], v[100:103], v[20:23]
	v_mfma_f32_16x16x32_bf16 v[24:27], v[202:205], v[100:103], v[24:27]
	v_mfma_f32_16x16x32_bf16 v[8:11], v[190:193], v[96:99], v[8:11]
	v_mfma_f32_16x16x32_bf16 v[16:19], v[194:197], v[96:99], v[16:19]
	v_mfma_f32_16x16x32_bf16 v[32:35], v[198:201], v[96:99], v[32:35]
	v_mfma_f32_16x16x32_bf16 v[48:51], v[202:205], v[96:99], v[48:51]
	v_mfma_f32_16x16x32_bf16 v[44:47], v[190:193], v[84:87], v[44:47]
	v_mfma_f32_16x16x32_bf16 v[40:43], v[194:197], v[84:87], v[40:43]
	v_mfma_f32_16x16x32_bf16 v[12:15], v[198:201], v[84:87], v[12:15]
	v_mfma_f32_16x16x32_bf16 v[4:7], v[202:205], v[84:87], v[4:7]
	v_mfma_f32_16x16x32_bf16 v[64:67], v[88:91], v[206:209], v[64:67]
	v_mfma_f32_16x16x32_bf16 v[60:63], v[80:83], v[206:209], v[60:63]
	v_mfma_f32_16x16x32_bf16 v[56:59], v[72:75], v[206:209], v[56:59]
	v_mfma_f32_16x16x32_bf16 v[52:55], v[76:79], v[206:209], v[52:55]
	v_mfma_f32_16x16x32_bf16 v[36:39], v[88:91], v[210:213], v[36:39]
	v_mfma_f32_16x16x32_bf16 v[28:31], v[80:83], v[210:213], v[28:31]
	v_mfma_f32_16x16x32_bf16 v[20:23], v[72:75], v[210:213], v[20:23]
	v_mfma_f32_16x16x32_bf16 v[24:27], v[76:79], v[210:213], v[24:27]
	v_mfma_f32_16x16x32_bf16 v[8:11], v[88:91], v[92:95], v[8:11]
	v_mfma_f32_16x16x32_bf16 v[16:19], v[80:83], v[92:95], v[16:19]
	v_mfma_f32_16x16x32_bf16 v[32:35], v[72:75], v[92:95], v[32:35]
	v_mfma_f32_16x16x32_bf16 v[48:51], v[76:79], v[92:95], v[48:51]
	v_mfma_f32_16x16x32_bf16 v[44:47], v[88:91], v[68:71], v[44:47]
	v_mfma_f32_16x16x32_bf16 v[40:43], v[80:83], v[68:71], v[40:43]
	v_mfma_f32_16x16x32_bf16 v[12:15], v[72:75], v[68:71], v[12:15]
	v_mfma_f32_16x16x32_bf16 v[4:7], v[76:79], v[68:71], v[4:7]
	s_cbranch_scc0 .LBB0_104
	v_add_u32_e32 v84, s23, v174
	v_add_u32_e32 v80, v84, v181
	s_waitcnt vmcnt(0)
	s_waitcnt vmcnt(0) lgkmcnt(0)
	s_barrier
	ds_read_b128 v[68:71], v80
	ds_read_b128 v[72:75], v80 offset:2048
	ds_read_b128 v[76:79], v80 offset:4096
	ds_read_b128 v[80:83], v80 offset:6144
	v_add_u32_e32 v96, v84, v180
	ds_read_b128 v[84:87], v96 offset:16384
	ds_read_b128 v[88:91], v96 offset:18432
	ds_read_b128 v[92:95], v96 offset:20480
	ds_read_b128 v[96:99], v96 offset:22528
	v_add_u32_e32 v139, s23, v175
	v_add_u32_e32 v144, v139, v181
	s_waitcnt lgkmcnt(3)
	v_mfma_f32_16x16x32_bf16 v[36:39], v[84:87], v[72:75], v[36:39]
	ds_read_b128 v[100:103], v144
	ds_read_b128 v[104:107], v144 offset:2048
	ds_read_b128 v[140:143], v144 offset:4096
	ds_read_b128 v[144:147], v144 offset:6144
	v_add_u32_e32 v139, v139, v180
	ds_read_b128 v[148:151], v139 offset:16384
	ds_read_b128 v[152:155], v139 offset:18432
	ds_read_b128 v[190:193], v139 offset:20480
	ds_read_b128 v[194:197], v139 offset:22528
	v_mfma_f32_16x16x32_bf16 v[64:67], v[84:87], v[68:71], v[64:67]
	v_readlane_b32 s26, v253, 25
	v_readlane_b32 s27, v253, 26
	v_mov_b32_e32 v139, v3
	s_waitcnt lgkmcnt(10)
	v_mfma_f32_16x16x32_bf16 v[60:63], v[88:91], v[68:71], v[60:63]
	s_add_i32 s24, s24, s0
	s_cmpk_lg_i32 s0, 0x200
	s_cbranch_scc1 .Ltail_skip_1
	s_cmpk_lt_i32 s24, 0x400
	s_cbranch_scc1 .Ltail_skip_1
	s_cmpk_ge_i32 s24, 0x600
	s_cbranch_scc1 .Ltail_skip_1
	v_readlane_b32 s24, v254, 61
	s_nop 3
	s_addk_i32 s24, 0x400
; template <int EPI>
; __device__ __forceinline__ void gemm_tile(const bf16_t* __restrict__ A, const int lda, const bf16_t* __restrict__ Bt, const int ldb,
;                                           const int K, const int m0, const int n0, void* Cout, const int ldc, char* lds, const int tid) {
;     ...
;     for (int ks = 0; ks < 2; ++ks)
; #pragma unroll
;       for (int m = 0; m < 4; ++m)
; #pragma unroll
;         for (int n = 0; n < 4; ++n) acc[m][n] = __builtin_amdgcn_mfma_f32_16x16x32_bf16(bfr[ks][n], af[ks][m], acc[m][n], 0, 0, 0);
;   }
;   if (EPI == EPI_RESID) {
;     float* C0 = (float*)Cout + (size_t)(m0 + wr * 64 + fr) * ldc + n0 + wc * 64 + fq * 4;
; #pragma unroll
;     for (int mh = 0; mh < 2; ++mh) {
;       f32x4 xin[2][4];
; #pragma unroll
;       for (int m = 0; m < 2; ++m)
; #pragma unroll
;         for (int n = 0; n < 4; ++n) xin[m][n] = *(const f32x4*)(C0 + (size_t)(mh * 2 + m) * 16 * ldc + n * 16);
.Ltail_skip_1:
	s_waitcnt lgkmcnt(9)
	v_mfma_f32_16x16x32_bf16 v[56:59], v[92:95], v[68:71], v[56:59]
	s_waitcnt lgkmcnt(8)
	v_mfma_f32_16x16x32_bf16 v[52:55], v[96:99], v[68:71], v[52:55]
	v_mfma_f32_16x16x32_bf16 v[8:11], v[84:87], v[76:79], v[8:11]
	v_mfma_f32_16x16x32_bf16 v[16:19], v[88:91], v[76:79], v[16:19]
	v_mfma_f32_16x16x32_bf16 v[68:71], v[92:95], v[76:79], v[32:35]
	v_mfma_f32_16x16x32_bf16 v[48:51], v[96:99], v[76:79], v[48:51]
	s_waitcnt lgkmcnt(3)
	v_mfma_f32_16x16x32_bf16 v[76:79], v[148:151], v[104:107], v[36:39]
	s_nop 2
	v_add_u32_e32 v36, s3, v182
	v_ashrrev_i32_e32 v37, 31, v36
	v_lshlrev_b64 v[36:37], 12, v[36:37]
	v_mfma_f32_16x16x32_bf16 v[20:23], v[92:95], v[72:75], v[20:23]
	v_lshl_add_u64 v[36:37], s[26:27], 0, v[36:37]
	s_ashr_i32 s3, s2, 31
	v_lshl_add_u64 v[36:37], s[2:3], 2, v[36:37]
	v_mfma_f32_16x16x32_bf16 v[28:31], v[88:91], v[72:75], v[28:31]
	v_lshl_add_u64 v[36:37], v[36:37], 0, v[2:3]
	v_lshl_add_u64 v[36:37], v[36:37], 0, v[138:139]
	s_mov_b32 s2, 0x10000
	v_mfma_f32_16x16x32_bf16 v[24:27], v[96:99], v[72:75], v[24:27]
	s_cmpk_gt_i32 s24, 0x427
	v_mfma_f32_16x16x32_bf16 v[44:47], v[84:87], v[80:83], v[44:47]
	v_mfma_f32_16x16x32_bf16 v[40:43], v[88:91], v[80:83], v[40:43]
	v_mfma_f32_16x16x32_bf16 v[72:75], v[92:95], v[80:83], v[12:15]
	s_waitcnt lgkmcnt(1)
	v_mfma_f32_16x16x32_bf16 v[84:87], v[190:193], v[104:107], v[20:23]
	s_waitcnt lgkmcnt(0)
	v_mfma_f32_16x16x32_bf16 v[20:23], v[194:197], v[140:143], v[48:51]
	s_nop 2
	v_add_co_u32_e32 v50, vcc, s2, v36
	v_mfma_f32_16x16x32_bf16 v[4:7], v[96:99], v[80:83], v[4:7]
	s_nop 0
	v_addc_co_u32_e32 v51, vcc, 0, v37, vcc
	s_mov_b32 s2, 0x20000
	v_mfma_f32_16x16x32_bf16 v[64:67], v[148:151], v[100:103], v[64:67]
	v_mfma_f32_16x16x32_bf16 v[60:63], v[152:155], v[100:103], v[60:63]
	v_mfma_f32_16x16x32_bf16 v[56:59], v[190:193], v[100:103], v[56:59]
	v_mfma_f32_16x16x32_bf16 v[52:55], v[194:197], v[100:103], v[52:55]
	v_mfma_f32_16x16x32_bf16 v[80:83], v[152:155], v[104:107], v[28:31]
	v_mfma_f32_16x16x32_bf16 v[88:91], v[194:197], v[104:107], v[24:27]
	v_mfma_f32_16x16x32_bf16 v[32:35], v[148:151], v[140:143], v[8:11]
	v_mfma_f32_16x16x32_bf16 v[28:31], v[152:155], v[140:143], v[16:19]
	v_mfma_f32_16x16x32_bf16 v[24:27], v[190:193], v[140:143], v[68:71]
	v_mfma_f32_16x16x32_bf16 v[16:19], v[148:151], v[144:147], v[44:47]
	v_mfma_f32_16x16x32_bf16 v[12:15], v[152:155], v[144:147], v[40:43]
	s_nop 2
	global_load_dwordx4 v[38:41], v[36:37], off
	global_load_dwordx4 v[42:45], v[36:37], off offset:64
	global_load_dwordx4 v[46:49], v[36:37], off offset:128
	global_load_dwordx4 v[68:71], v[36:37], off offset:192
	v_mfma_f32_16x16x32_bf16 v[8:11], v[190:193], v[144:147], v[72:75]
	s_nop 2
	global_load_dwordx4 v[72:75], v[50:51], off
	global_load_dwordx4 v[92:95], v[50:51], off offset:64
	global_load_dwordx4 v[96:99], v[50:51], off offset:128
	global_load_dwordx4 v[100:103], v[50:51], off offset:192
	s_waitcnt vmcnt(7)
	s_nop 0
	v_pk_fma_f32 v[40:41], v[40:41], s[78:79], v[66:67] op_sel_hi:[1,0,1]
	v_pk_fma_f32 v[38:39], v[38:39], s[78:79], v[64:65] op_sel_hi:[1,0,1]
	s_waitcnt vmcnt(6)
	s_waitcnt vmcnt(5)
	s_waitcnt vmcnt(4)
	s_waitcnt vmcnt(3)
	s_waitcnt vmcnt(2)
	s_waitcnt vmcnt(1)
	s_waitcnt vmcnt(0)
; template <int EPI>
; __device__ __forceinline__ void gemm_tile(const bf16_t* __restrict__ A, const int lda, const bf16_t* __restrict__ Bt, const int ldb,
;                                           const int K, const int m0, const int n0, void* Cout, const int ldc, char* lds, const int tid) {
;     ...
;         for (int n = 0; n < 4; ++n) xin[m][n] = *(const f32x4*)(C0 + (size_t)(mh * 2 + m) * 16 * ldc + n * 16);
; #pragma unroll
;       for (int m = 0; m < 2; ++m)
; #pragma unroll
;         for (int n = 0; n < 4; ++n) asm volatile("" : "+v"(xin[m][n]));
; #pragma unroll
;       for (int m = 0; m < 2; ++m)
; #pragma unroll
;         for (int n = 0; n < 4; ++n) *(f32x4*)(C0 + (size_t)(mh * 2 + m) * 16 * ldc + n * 16) = xin[m][n] * ALPHA + acc[mh * 2 + m][n];
;     }
;     return;
	global_store_dwordx4 v[36:37], v[38:41], off
	v_mfma_f32_16x16x32_bf16 v[4:7], v[194:197], v[144:147], v[4:7]
	s_nop 0
	v_fma_f32 v40, v44, s78, v62
	v_fma_f32 v41, v45, s78, v63
	v_pk_fma_f32 v[38:39], v[42:43], s[78:79], v[60:61] op_sel_hi:[1,0,1]
	global_store_dwordx4 v[36:37], v[38:41], off offset:64
	s_nop 1
	v_pk_fma_f32 v[40:41], v[48:49], s[78:79], v[58:59] op_sel_hi:[1,0,1]
	v_pk_fma_f32 v[38:39], v[46:47], s[78:79], v[56:57] op_sel_hi:[1,0,1]
	global_store_dwordx4 v[36:37], v[38:41], off offset:128
	s_nop 1
	v_pk_fma_f32 v[40:41], v[70:71], s[78:79], v[54:55] op_sel_hi:[1,0,1]
	v_pk_fma_f32 v[38:39], v[68:69], s[78:79], v[52:53] op_sel_hi:[1,0,1]
	global_store_dwordx4 v[36:37], v[38:41], off offset:192
	v_add_co_u32_e32 v70, vcc, s2, v36
	s_nop 0
	v_pk_fma_f32 v[40:41], v[74:75], s[78:79], v[78:79] op_sel_hi:[1,0,1]
	v_pk_fma_f32 v[38:39], v[72:73], s[78:79], v[76:77] op_sel_hi:[1,0,1]
	global_store_dwordx4 v[50:51], v[38:41], off
	v_addc_co_u32_e32 v71, vcc, 0, v37, vcc
	s_nop 0
	v_pk_fma_f32 v[40:41], v[94:95], s[78:79], v[82:83] op_sel_hi:[1,0,1]
	v_pk_fma_f32 v[38:39], v[92:93], s[78:79], v[80:81] op_sel_hi:[1,0,1]
	global_store_dwordx4 v[50:51], v[38:41], off offset:64
	s_mov_b32 s2, 0x30000
	v_add_co_u32_e32 v36, vcc, s2, v36
	v_pk_fma_f32 v[40:41], v[98:99], s[78:79], v[86:87] op_sel_hi:[1,0,1]
	v_pk_fma_f32 v[38:39], v[96:97], s[78:79], v[84:85] op_sel_hi:[1,0,1]
	global_store_dwordx4 v[50:51], v[38:41], off offset:128
	v_addc_co_u32_e32 v37, vcc, 0, v37, vcc
	s_nop 0
	v_pk_fma_f32 v[40:41], v[102:103], s[78:79], v[90:91] op_sel_hi:[1,0,1]
	v_pk_fma_f32 v[38:39], v[100:101], s[78:79], v[88:89] op_sel_hi:[1,0,1]
	global_store_dwordx4 v[50:51], v[38:41], off offset:192
	global_load_dwordx4 v[38:41], v[70:71], off
	s_nop 0
	global_load_dwordx4 v[42:45], v[70:71], off offset:64
	global_load_dwordx4 v[46:49], v[70:71], off offset:128
	global_load_dwordx4 v[50:53], v[70:71], off offset:192
	global_load_dwordx4 v[54:57], v[36:37], off
	global_load_dwordx4 v[58:61], v[36:37], off offset:64
	global_load_dwordx4 v[62:65], v[36:37], off offset:128
	global_load_dwordx4 v[66:69], v[36:37], off offset:192
	s_waitcnt vmcnt(7)
	s_waitcnt vmcnt(6)
	s_waitcnt vmcnt(5)
	s_waitcnt vmcnt(4)
	s_waitcnt vmcnt(3)
	s_waitcnt vmcnt(2)
	s_waitcnt vmcnt(1)
	s_waitcnt vmcnt(0)
	v_pk_fma_f32 v[34:35], v[40:41], s[78:79], v[34:35] op_sel_hi:[1,0,1]
	v_pk_fma_f32 v[32:33], v[38:39], s[78:79], v[32:33] op_sel_hi:[1,0,1]
	v_pk_fma_f32 v[30:31], v[44:45], s[78:79], v[30:31] op_sel_hi:[1,0,1]
	v_pk_fma_f32 v[28:29], v[42:43], s[78:79], v[28:29] op_sel_hi:[1,0,1]
	v_pk_fma_f32 v[26:27], v[48:49], s[78:79], v[26:27] op_sel_hi:[1,0,1]
	v_pk_fma_f32 v[24:25], v[46:47], s[78:79], v[24:25] op_sel_hi:[1,0,1]
	v_pk_fma_f32 v[22:23], v[52:53], s[78:79], v[22:23] op_sel_hi:[1,0,1]
	v_pk_fma_f32 v[20:21], v[50:51], s[78:79], v[20:21] op_sel_hi:[1,0,1]
	v_pk_fma_f32 v[18:19], v[56:57], s[78:79], v[18:19] op_sel_hi:[1,0,1]
	v_pk_fma_f32 v[16:17], v[54:55], s[78:79], v[16:17] op_sel_hi:[1,0,1]
	v_pk_fma_f32 v[14:15], v[60:61], s[78:79], v[14:15] op_sel_hi:[1,0,1]
	v_pk_fma_f32 v[12:13], v[58:59], s[78:79], v[12:13] op_sel_hi:[1,0,1]
	v_pk_fma_f32 v[10:11], v[64:65], s[78:79], v[10:11] op_sel_hi:[1,0,1]
	v_pk_fma_f32 v[8:9], v[62:63], s[78:79], v[8:9] op_sel_hi:[1,0,1]
	v_pk_fma_f32 v[6:7], v[68:69], s[78:79], v[6:7] op_sel_hi:[1,0,1]
	v_pk_fma_f32 v[4:5], v[66:67], s[78:79], v[4:5] op_sel_hi:[1,0,1]
	global_store_dwordx4 v[70:71], v[32:35], off
	global_store_dwordx4 v[70:71], v[28:31], off offset:64
	global_store_dwordx4 v[70:71], v[24:27], off offset:128
	global_store_dwordx4 v[70:71], v[20:23], off offset:192
	global_store_dwordx4 v[36:37], v[16:19], off
	global_store_dwordx4 v[36:37], v[12:15], off offset:64
	global_store_dwordx4 v[36:37], v[8:11], off offset:128
	global_store_dwordx4 v[36:37], v[4:7], off offset:192
	s_cbranch_scc0 .LBB0_103

; template <int EPI>
; __device__ __forceinline__ void gemm_tile(const bf16_t* __restrict__ A, const int lda, const bf16_t* __restrict__ Bt, const int ldb,
;                                           const int K, const int m0, const int n0, void* Cout, const int ldc, char* lds, const int tid) {
;     ...
;   for (int kt = 0; kt < nt; ++kt) {
;     asm volatile("s_waitcnt vmcnt(0)" ::: "memory");
;     __syncthreads();
;     if (kt + 1 < nt) stageB(kt + 1, (kt + 1) & 1);
;     const char* sa = lds + (kt & 1) * 32768;
;     const char* sb = sa + 16384;
;     bf16x8 af[2][4], bfr[2][4];
; #pragma unroll
;     for (int ks = 0; ks < 2; ++ks) {
; #pragma unroll
;       for (int m = 0; m < 4; ++m) af[ks][m] = *(const bf16x8*)(sa + (wr * 64 + m * 16 + fr) * 128 + (ks ? xk1 : xk0));
; #pragma unroll
;       for (int n = 0; n < 4; ++n) bfr[ks][n] = *(const bf16x8*)(sb + (wc * 64 + n * 16 + fr) * 128 + (ks ? xk1 : xk0));
;     }
;     if (kt + 1 < nt) stageA(kt + 1, (kt + 1) & 1);
; #pragma unroll
;     for (int ks = 0; ks < 2; ++ks)
; #pragma unroll
;       for (int m = 0; m < 4; ++m)
; #pragma unroll
;         for (int n = 0; n < 4; ++n) acc[m][n] = __builtin_amdgcn_mfma_f32_16x16x32_bf16(bfr[ks][n], af[ks][m], acc[m][n], 0, 0, 0);
;   }
; template <int EPI>
; __device__ __forceinline__ void gemm_phase(const bf16_t* A, int lda, const bf16_t* Bt, int ldb, int K, int ntn, void* C, int ldc, char* lds, int bid, int nb, const int tid) {
;     ...
;   for (int L = pos; L < ntiles; L += nb) {
;     int mt, nn;
;     if (EPI == EPI_SWIGLU) { mt = L / ntn; nn = L % ntn; }
;     else { const int gid = L / nig, fm = gid * GM, gsz = min(nM - fm, GM), rem = L - gid * nig; mt = fm + rem % gsz; nn = rem / gsz; }
.LBB0_125:
	s_add_i32 s25, s26, 0x8000
	s_and_b32 s23, s25, 0x8000
	v_add_u32_e32 v139, s23, v176
	v_add_u32_e32 v70, 0x4000, v139
	v_lshl_add_u64 v[68:69], v[140:141], 0, s[34:35]
	v_readfirstlane_b32 s27, v70
	v_add_u32_e32 v70, 0x5000, v139
	s_mov_b32 m0, s27
	v_readfirstlane_b32 s27, v70
	v_add_u32_e32 v70, 0x6000, v139
	s_waitcnt vmcnt(0)
	s_waitcnt vmcnt(0) lgkmcnt(0)
	s_barrier
	global_load_lds_dwordx4 v[68:69], off
	v_lshl_add_u64 v[68:69], v[142:143], 0, s[34:35]
	s_mov_b32 m0, s27
	v_readfirstlane_b32 s27, v70
	v_add_u32_e32 v70, 0x7000, v139
	global_load_lds_dwordx4 v[68:69], off
	v_lshl_add_u64 v[68:69], v[144:145], 0, s[34:35]
	s_mov_b32 m0, s27
	v_readfirstlane_b32 s27, v70
	global_load_lds_dwordx4 v[68:69], off
	v_lshl_add_u64 v[68:69], v[146:147], 0, s[34:35]
	s_mov_b32 m0, s27
	s_and_b32 s26, s26, 0x8000
	global_load_lds_dwordx4 v[68:69], off
	v_or_b32_e32 v68, s26, v174
	v_add_u32_e32 v69, v68, v181
	v_add_u32_e32 v68, v68, v180
	v_or_b32_e32 v72, s26, v175
	v_readfirstlane_b32 s26, v139
	v_add_u32_e32 v168, 0x1000, v139
	ds_read_b128 v[104:107], v69
	ds_read_b128 v[100:103], v69 offset:2048
	ds_read_b128 v[96:99], v69 offset:4096
	ds_read_b128 v[84:87], v69 offset:6144
	ds_read_b128 v[184:187], v68 offset:16384
	ds_read_b128 v[188:191], v68 offset:18432
	ds_read_b128 v[192:195], v68 offset:20480
	ds_read_b128 v[196:199], v68 offset:22528
	v_add_u32_e32 v68, v72, v181
	v_add_u32_e32 v76, v72, v180
	v_lshl_add_u64 v[158:159], v[148:149], 0, s[34:35]
	s_mov_b32 m0, s26
	v_readfirstlane_b32 s26, v168
	v_add_u32_e32 v168, 0x2000, v139
	ds_read_b128 v[200:203], v68
	ds_read_b128 v[204:207], v68 offset:2048
	ds_read_b128 v[92:95], v68 offset:4096
	ds_read_b128 v[68:71], v68 offset:6144
	ds_read_b128 v[88:91], v76 offset:16384
	ds_read_b128 v[80:83], v76 offset:18432
	ds_read_b128 v[72:75], v76 offset:20480
	ds_read_b128 v[76:79], v76 offset:22528
	global_load_lds_dwordx4 v[158:159], off
	v_lshl_add_u64 v[158:159], v[150:151], 0, s[34:35]
	s_mov_b32 m0, s26
	v_readfirstlane_b32 s26, v168
	v_add_u32_e32 v139, 0x3000, v139
	global_load_lds_dwordx4 v[158:159], off
	v_lshl_add_u64 v[158:159], v[152:153], 0, s[34:35]
	s_mov_b32 m0, s26
	v_readfirstlane_b32 s26, v139
	global_load_lds_dwordx4 v[158:159], off
	v_lshl_add_u64 v[158:159], v[154:155], 0, s[34:35]
	s_mov_b32 m0, s26
	s_waitcnt lgkmcnt(0)
	v_mfma_f32_16x16x32_bf16 v[64:67], v[184:187], v[104:107], v[64:67]
	global_load_lds_dwordx4 v[158:159], off
	s_add_u32 s34, s34, 0x80
	v_mfma_f32_16x16x32_bf16 v[60:63], v[188:191], v[104:107], v[60:63]
	s_addc_u32 s35, s35, 0
	s_cmpk_eq_i32 s34, 0x780
	s_mov_b32 s26, s25
	v_mfma_f32_16x16x32_bf16 v[56:59], v[192:195], v[104:107], v[56:59]
	v_mfma_f32_16x16x32_bf16 v[52:55], v[196:199], v[104:107], v[52:55]
	v_mfma_f32_16x16x32_bf16 v[36:39], v[184:187], v[100:103], v[36:39]
	v_mfma_f32_16x16x32_bf16 v[28:31], v[188:191], v[100:103], v[28:31]
	v_mfma_f32_16x16x32_bf16 v[20:23], v[192:195], v[100:103], v[20:23]
	v_mfma_f32_16x16x32_bf16 v[24:27], v[196:199], v[100:103], v[24:27]
	v_mfma_f32_16x16x32_bf16 v[8:11], v[184:187], v[96:99], v[8:11]
	v_mfma_f32_16x16x32_bf16 v[16:19], v[188:191], v[96:99], v[16:19]
	v_mfma_f32_16x16x32_bf16 v[32:35], v[192:195], v[96:99], v[32:35]
	v_mfma_f32_16x16x32_bf16 v[48:51], v[196:199], v[96:99], v[48:51]
	v_mfma_f32_16x16x32_bf16 v[44:47], v[184:187], v[84:87], v[44:47]
	v_mfma_f32_16x16x32_bf16 v[40:43], v[188:191], v[84:87], v[40:43]
	v_mfma_f32_16x16x32_bf16 v[12:15], v[192:195], v[84:87], v[12:15]
	v_mfma_f32_16x16x32_bf16 v[4:7], v[196:199], v[84:87], v[4:7]
	v_mfma_f32_16x16x32_bf16 v[64:67], v[88:91], v[200:203], v[64:67]
	v_mfma_f32_16x16x32_bf16 v[60:63], v[80:83], v[200:203], v[60:63]
	v_mfma_f32_16x16x32_bf16 v[56:59], v[72:75], v[200:203], v[56:59]
	v_mfma_f32_16x16x32_bf16 v[52:55], v[76:79], v[200:203], v[52:55]
	v_mfma_f32_16x16x32_bf16 v[36:39], v[88:91], v[204:207], v[36:39]
	v_mfma_f32_16x16x32_bf16 v[28:31], v[80:83], v[204:207], v[28:31]
	v_mfma_f32_16x16x32_bf16 v[20:23], v[72:75], v[204:207], v[20:23]
	v_mfma_f32_16x16x32_bf16 v[24:27], v[76:79], v[204:207], v[24:27]
	v_mfma_f32_16x16x32_bf16 v[8:11], v[88:91], v[92:95], v[8:11]
	v_mfma_f32_16x16x32_bf16 v[16:19], v[80:83], v[92:95], v[16:19]
	v_mfma_f32_16x16x32_bf16 v[32:35], v[72:75], v[92:95], v[32:35]
	v_mfma_f32_16x16x32_bf16 v[48:51], v[76:79], v[92:95], v[48:51]
	v_mfma_f32_16x16x32_bf16 v[44:47], v[88:91], v[68:71], v[44:47]
	v_mfma_f32_16x16x32_bf16 v[40:43], v[80:83], v[68:71], v[40:43]
	v_mfma_f32_16x16x32_bf16 v[12:15], v[72:75], v[68:71], v[12:15]
	v_mfma_f32_16x16x32_bf16 v[4:7], v[76:79], v[68:71], v[4:7]
	s_cbranch_scc0 .LBB0_125
	v_add_u32_e32 v84, s23, v174
	v_add_u32_e32 v80, v84, v181
	s_waitcnt vmcnt(0)
	s_waitcnt vmcnt(0) lgkmcnt(0)
	s_barrier
	ds_read_b128 v[68:71], v80
	ds_read_b128 v[72:75], v80 offset:2048
	ds_read_b128 v[76:79], v80 offset:4096
	ds_read_b128 v[80:83], v80 offset:6144
	v_add_u32_e32 v96, v84, v180
	ds_read_b128 v[84:87], v96 offset:16384
	ds_read_b128 v[88:91], v96 offset:18432
	ds_read_b128 v[92:95], v96 offset:20480
	ds_read_b128 v[96:99], v96 offset:22528
	v_add_u32_e32 v139, s23, v175
	v_add_u32_e32 v144, v139, v181
	s_waitcnt lgkmcnt(3)
	v_mfma_f32_16x16x32_bf16 v[36:39], v[84:87], v[72:75], v[36:39]
	ds_read_b128 v[100:103], v144
	ds_read_b128 v[104:107], v144 offset:2048
	ds_read_b128 v[140:143], v144 offset:4096
	ds_read_b128 v[144:147], v144 offset:6144
	v_add_u32_e32 v139, v139, v180
	ds_read_b128 v[148:151], v139 offset:16384
	ds_read_b128 v[152:155], v139 offset:18432
	ds_read_b128 v[184:187], v139 offset:20480
	ds_read_b128 v[188:191], v139 offset:22528
	v_mfma_f32_16x16x32_bf16 v[64:67], v[84:87], v[68:71], v[64:67]
	v_readlane_b32 s26, v253, 25
	v_readlane_b32 s27, v253, 26
	v_mov_b32_e32 v139, v3
	s_waitcnt lgkmcnt(10)
	v_mfma_f32_16x16x32_bf16 v[60:63], v[88:91], v[68:71], v[60:63]
	s_add_i32 s24, s24, s0
	s_cmpk_lg_i32 s0, 0x200
	s_cbranch_scc1 .Ltail_skip_2
	s_cmpk_lt_i32 s24, 0x400
	s_cbranch_scc1 .Ltail_skip_2
	s_cmpk_ge_i32 s24, 0x600
	s_cbranch_scc1 .Ltail_skip_2
	v_readlane_b32 s24, v254, 61
	s_nop 3
	s_addk_i32 s24, 0x400
; template <int EPI>
; __device__ __forceinline__ void gemm_tile(const bf16_t* __restrict__ A, const int lda, const bf16_t* __restrict__ Bt, const int ldb,
;                                           const int K, const int m0, const int n0, void* Cout, const int ldc, char* lds, const int tid) {
;     ...
;     for (int ks = 0; ks < 2; ++ks)
; #pragma unroll
;       for (int m = 0; m < 4; ++m)
; #pragma unroll
;         for (int n = 0; n < 4; ++n) acc[m][n] = __builtin_amdgcn_mfma_f32_16x16x32_bf16(bfr[ks][n], af[ks][m], acc[m][n], 0, 0, 0);
;   }
;   if (EPI == EPI_RESID) {
;     float* C0 = (float*)Cout + (size_t)(m0 + wr * 64 + fr) * ldc + n0 + wc * 64 + fq * 4;
; #pragma unroll
;     for (int mh = 0; mh < 2; ++mh) {
;       f32x4 xin[2][4];
; #pragma unroll
;       for (int m = 0; m < 2; ++m)
; #pragma unroll
;         for (int n = 0; n < 4; ++n) xin[m][n] = *(const f32x4*)(C0 + (size_t)(mh * 2 + m) * 16 * ldc + n * 16);
.Ltail_skip_2:
	s_waitcnt lgkmcnt(9)
	v_mfma_f32_16x16x32_bf16 v[56:59], v[92:95], v[68:71], v[56:59]
	s_waitcnt lgkmcnt(8)
	v_mfma_f32_16x16x32_bf16 v[52:55], v[96:99], v[68:71], v[52:55]
	v_mfma_f32_16x16x32_bf16 v[8:11], v[84:87], v[76:79], v[8:11]
	v_mfma_f32_16x16x32_bf16 v[16:19], v[88:91], v[76:79], v[16:19]
	v_mfma_f32_16x16x32_bf16 v[68:71], v[92:95], v[76:79], v[32:35]
	v_mfma_f32_16x16x32_bf16 v[48:51], v[96:99], v[76:79], v[48:51]
	s_waitcnt lgkmcnt(3)
	v_mfma_f32_16x16x32_bf16 v[76:79], v[148:151], v[104:107], v[36:39]
	s_nop 2
	v_add_u32_e32 v36, s3, v182
	v_ashrrev_i32_e32 v37, 31, v36
	v_lshlrev_b64 v[36:37], 12, v[36:37]
	v_mfma_f32_16x16x32_bf16 v[20:23], v[92:95], v[72:75], v[20:23]
	v_lshl_add_u64 v[36:37], s[26:27], 0, v[36:37]
	s_ashr_i32 s3, s2, 31
	v_lshl_add_u64 v[36:37], s[2:3], 2, v[36:37]
	v_mfma_f32_16x16x32_bf16 v[28:31], v[88:91], v[72:75], v[28:31]
	v_lshl_add_u64 v[36:37], v[36:37], 0, v[2:3]
	v_lshl_add_u64 v[36:37], v[36:37], 0, v[138:139]
	s_mov_b32 s2, 0x10000
	v_mfma_f32_16x16x32_bf16 v[24:27], v[96:99], v[72:75], v[24:27]
	s_cmpk_gt_i32 s24, 0x427
	v_mfma_f32_16x16x32_bf16 v[44:47], v[84:87], v[80:83], v[44:47]
	v_mfma_f32_16x16x32_bf16 v[40:43], v[88:91], v[80:83], v[40:43]
	v_mfma_f32_16x16x32_bf16 v[72:75], v[92:95], v[80:83], v[12:15]
	s_waitcnt lgkmcnt(1)
	v_mfma_f32_16x16x32_bf16 v[84:87], v[184:187], v[104:107], v[20:23]
	s_waitcnt lgkmcnt(0)
	v_mfma_f32_16x16x32_bf16 v[20:23], v[188:191], v[140:143], v[48:51]
	s_nop 2
	v_add_co_u32_e32 v50, vcc, s2, v36
	v_mfma_f32_16x16x32_bf16 v[4:7], v[96:99], v[80:83], v[4:7]
	s_nop 0
	v_addc_co_u32_e32 v51, vcc, 0, v37, vcc
	s_mov_b32 s2, 0x20000
	v_mfma_f32_16x16x32_bf16 v[64:67], v[148:151], v[100:103], v[64:67]
	v_mfma_f32_16x16x32_bf16 v[60:63], v[152:155], v[100:103], v[60:63]
	v_mfma_f32_16x16x32_bf16 v[56:59], v[184:187], v[100:103], v[56:59]
	v_mfma_f32_16x16x32_bf16 v[52:55], v[188:191], v[100:103], v[52:55]
	v_mfma_f32_16x16x32_bf16 v[80:83], v[152:155], v[104:107], v[28:31]
	v_mfma_f32_16x16x32_bf16 v[88:91], v[188:191], v[104:107], v[24:27]
	v_mfma_f32_16x16x32_bf16 v[32:35], v[148:151], v[140:143], v[8:11]
	v_mfma_f32_16x16x32_bf16 v[28:31], v[152:155], v[140:143], v[16:19]
	v_mfma_f32_16x16x32_bf16 v[24:27], v[184:187], v[140:143], v[68:71]
	v_mfma_f32_16x16x32_bf16 v[16:19], v[148:151], v[144:147], v[44:47]
	v_mfma_f32_16x16x32_bf16 v[12:15], v[152:155], v[144:147], v[40:43]
	s_nop 2
	global_load_dwordx4 v[38:41], v[36:37], off
	global_load_dwordx4 v[42:45], v[36:37], off offset:64
	global_load_dwordx4 v[46:49], v[36:37], off offset:128
	global_load_dwordx4 v[68:71], v[36:37], off offset:192
	v_mfma_f32_16x16x32_bf16 v[8:11], v[184:187], v[144:147], v[72:75]
	s_nop 2
	global_load_dwordx4 v[72:75], v[50:51], off
	global_load_dwordx4 v[92:95], v[50:51], off offset:64
	global_load_dwordx4 v[96:99], v[50:51], off offset:128
	global_load_dwordx4 v[100:103], v[50:51], off offset:192
	s_waitcnt vmcnt(7)
	s_nop 0
	v_pk_fma_f32 v[40:41], v[40:41], s[78:79], v[66:67] op_sel_hi:[1,0,1]
	v_pk_fma_f32 v[38:39], v[38:39], s[78:79], v[64:65] op_sel_hi:[1,0,1]
	s_waitcnt vmcnt(6)
	s_waitcnt vmcnt(5)
	s_waitcnt vmcnt(4)
	s_waitcnt vmcnt(3)
	s_waitcnt vmcnt(2)
	s_waitcnt vmcnt(1)
	s_waitcnt vmcnt(0)
; template <int EPI>
; __device__ __forceinline__ void gemm_tile(const bf16_t* __restrict__ A, const int lda, const bf16_t* __restrict__ Bt, const int ldb,
;                                           const int K, const int m0, const int n0, void* Cout, const int ldc, char* lds, const int tid) {
;     ...
;         for (int n = 0; n < 4; ++n) xin[m][n] = *(const f32x4*)(C0 + (size_t)(mh * 2 + m) * 16 * ldc + n * 16);
; #pragma unroll
;       for (int m = 0; m < 2; ++m)
; #pragma unroll
;         for (int n = 0; n < 4; ++n) asm volatile("" : "+v"(xin[m][n]));
; #pragma unroll
;       for (int m = 0; m < 2; ++m)
; #pragma unroll
;         for (int n = 0; n < 4; ++n) *(f32x4*)(C0 + (size_t)(mh * 2 + m) * 16 * ldc + n * 16) = xin[m][n] * ALPHA + acc[mh * 2 + m][n];
;     }
;     return;
	global_store_dwordx4 v[36:37], v[38:41], off
	v_mfma_f32_16x16x32_bf16 v[4:7], v[188:191], v[144:147], v[4:7]
	s_nop 0
	v_fma_f32 v40, v44, s78, v62
	v_fma_f32 v41, v45, s78, v63
	v_pk_fma_f32 v[38:39], v[42:43], s[78:79], v[60:61] op_sel_hi:[1,0,1]
	global_store_dwordx4 v[36:37], v[38:41], off offset:64
	s_nop 1
	v_pk_fma_f32 v[40:41], v[48:49], s[78:79], v[58:59] op_sel_hi:[1,0,1]
	v_pk_fma_f32 v[38:39], v[46:47], s[78:79], v[56:57] op_sel_hi:[1,0,1]
	global_store_dwordx4 v[36:37], v[38:41], off offset:128
	s_nop 1
	v_pk_fma_f32 v[40:41], v[70:71], s[78:79], v[54:55] op_sel_hi:[1,0,1]
	v_pk_fma_f32 v[38:39], v[68:69], s[78:79], v[52:53] op_sel_hi:[1,0,1]
	global_store_dwordx4 v[36:37], v[38:41], off offset:192
	v_add_co_u32_e32 v70, vcc, s2, v36
	s_nop 0
	v_pk_fma_f32 v[40:41], v[74:75], s[78:79], v[78:79] op_sel_hi:[1,0,1]
	v_pk_fma_f32 v[38:39], v[72:73], s[78:79], v[76:77] op_sel_hi:[1,0,1]
	global_store_dwordx4 v[50:51], v[38:41], off
	v_addc_co_u32_e32 v71, vcc, 0, v37, vcc
	s_nop 0
	v_pk_fma_f32 v[40:41], v[94:95], s[78:79], v[82:83] op_sel_hi:[1,0,1]
	v_pk_fma_f32 v[38:39], v[92:93], s[78:79], v[80:81] op_sel_hi:[1,0,1]
	global_store_dwordx4 v[50:51], v[38:41], off offset:64
	s_mov_b32 s2, 0x30000
	v_add_co_u32_e32 v36, vcc, s2, v36
	v_pk_fma_f32 v[40:41], v[98:99], s[78:79], v[86:87] op_sel_hi:[1,0,1]
	v_pk_fma_f32 v[38:39], v[96:97], s[78:79], v[84:85] op_sel_hi:[1,0,1]
	global_store_dwordx4 v[50:51], v[38:41], off offset:128
	v_addc_co_u32_e32 v37, vcc, 0, v37, vcc
	s_nop 0
	v_pk_fma_f32 v[40:41], v[102:103], s[78:79], v[90:91] op_sel_hi:[1,0,1]
	v_pk_fma_f32 v[38:39], v[100:101], s[78:79], v[88:89] op_sel_hi:[1,0,1]
	global_store_dwordx4 v[50:51], v[38:41], off offset:192
	global_load_dwordx4 v[38:41], v[70:71], off
	s_nop 0
	global_load_dwordx4 v[42:45], v[70:71], off offset:64
	global_load_dwordx4 v[46:49], v[70:71], off offset:128
	global_load_dwordx4 v[50:53], v[70:71], off offset:192
	global_load_dwordx4 v[54:57], v[36:37], off
	global_load_dwordx4 v[58:61], v[36:37], off offset:64
	global_load_dwordx4 v[62:65], v[36:37], off offset:128
	global_load_dwordx4 v[66:69], v[36:37], off offset:192
	s_waitcnt vmcnt(7)
	s_waitcnt vmcnt(6)
	s_waitcnt vmcnt(5)
	s_waitcnt vmcnt(4)
	s_waitcnt vmcnt(3)
	s_waitcnt vmcnt(2)
	s_waitcnt vmcnt(1)
	s_waitcnt vmcnt(0)
	v_pk_fma_f32 v[34:35], v[40:41], s[78:79], v[34:35] op_sel_hi:[1,0,1]
	v_pk_fma_f32 v[32:33], v[38:39], s[78:79], v[32:33] op_sel_hi:[1,0,1]
	v_pk_fma_f32 v[30:31], v[44:45], s[78:79], v[30:31] op_sel_hi:[1,0,1]
	v_pk_fma_f32 v[28:29], v[42:43], s[78:79], v[28:29] op_sel_hi:[1,0,1]
	v_pk_fma_f32 v[26:27], v[48:49], s[78:79], v[26:27] op_sel_hi:[1,0,1]
	v_pk_fma_f32 v[24:25], v[46:47], s[78:79], v[24:25] op_sel_hi:[1,0,1]
	v_pk_fma_f32 v[22:23], v[52:53], s[78:79], v[22:23] op_sel_hi:[1,0,1]
	v_pk_fma_f32 v[20:21], v[50:51], s[78:79], v[20:21] op_sel_hi:[1,0,1]
	v_pk_fma_f32 v[18:19], v[56:57], s[78:79], v[18:19] op_sel_hi:[1,0,1]
	v_pk_fma_f32 v[16:17], v[54:55], s[78:79], v[16:17] op_sel_hi:[1,0,1]
	v_pk_fma_f32 v[14:15], v[60:61], s[78:79], v[14:15] op_sel_hi:[1,0,1]
	v_pk_fma_f32 v[12:13], v[58:59], s[78:79], v[12:13] op_sel_hi:[1,0,1]
	v_pk_fma_f32 v[10:11], v[64:65], s[78:79], v[10:11] op_sel_hi:[1,0,1]
	v_pk_fma_f32 v[8:9], v[62:63], s[78:79], v[8:9] op_sel_hi:[1,0,1]
	v_pk_fma_f32 v[6:7], v[68:69], s[78:79], v[6:7] op_sel_hi:[1,0,1]
	v_pk_fma_f32 v[4:5], v[66:67], s[78:79], v[4:5] op_sel_hi:[1,0,1]
	global_store_dwordx4 v[70:71], v[32:35], off
	global_store_dwordx4 v[70:71], v[28:31], off offset:64
	global_store_dwordx4 v[70:71], v[24:27], off offset:128
	global_store_dwordx4 v[70:71], v[20:23], off offset:192
	global_store_dwordx4 v[36:37], v[16:19], off
	global_store_dwordx4 v[36:37], v[12:15], off offset:64
	global_store_dwordx4 v[36:37], v[8:11], off offset:128
	global_store_dwordx4 v[36:37], v[4:7], off offset:192
	s_cbranch_scc0 .LBB0_124

; template <int EPI>
; __device__ __forceinline__ void gemm_tile(const bf16_t* __restrict__ A, const int lda, const bf16_t* __restrict__ Bt, const int ldb,
;                                           const int K, const int m0, const int n0, void* Cout, const int ldc, char* lds, const int tid) {
;     ...
;   for (int kt = 0; kt < nt; ++kt) {
;     asm volatile("s_waitcnt vmcnt(0)" ::: "memory");
;     __syncthreads();
;     if (kt + 1 < nt) stageB(kt + 1, (kt + 1) & 1);
;     const char* sa = lds + (kt & 1) * 32768;
;     const char* sb = sa + 16384;
;     bf16x8 af[2][4], bfr[2][4];
; #pragma unroll
;     for (int ks = 0; ks < 2; ++ks) {
; #pragma unroll
;       for (int m = 0; m < 4; ++m) af[ks][m] = *(const bf16x8*)(sa + (wr * 64 + m * 16 + fr) * 128 + (ks ? xk1 : xk0));
; #pragma unroll
;       for (int n = 0; n < 4; ++n) bfr[ks][n] = *(const bf16x8*)(sb + (wc * 64 + n * 16 + fr) * 128 + (ks ? xk1 : xk0));
;     }
;     if (kt + 1 < nt) stageA(kt + 1, (kt + 1) & 1);
; #pragma unroll
;     for (int ks = 0; ks < 2; ++ks)
; #pragma unroll
;       for (int m = 0; m < 4; ++m)
; #pragma unroll
;         for (int n = 0; n < 4; ++n) acc[m][n] = __builtin_amdgcn_mfma_f32_16x16x32_bf16(bfr[ks][n], af[ks][m], acc[m][n], 0, 0, 0);
;   }
; template <int EPI>
; __device__ __forceinline__ void gemm_phase(const bf16_t* A, int lda, const bf16_t* Bt, int ldb, int K, int ntn, void* C, int ldc, char* lds, int bid, int nb, const int tid) {
;     ...
;   for (int L = pos; L < ntiles; L += nb) {
;     int mt, nn;
;     if (EPI == EPI_SWIGLU) { mt = L / ntn; nn = L % ntn; }
;     else { const int gid = L / nig, fm = gid * GM, gsz = min(nM - fm, GM), rem = L - gid * nig; mt = fm + rem % gsz; nn = rem / gsz; }
.LBB0_649:
	s_add_i32 s24, s25, 0x8000
	s_and_b32 s26, s24, 0x8000
	v_add_u32_e32 v2, s26, v177
	v_add_u32_e32 v70, 0x4000, v2
	v_lshl_add_u64 v[68:69], v[140:141], 0, s[34:35]
	v_readfirstlane_b32 s26, v70
	v_add_u32_e32 v70, 0x5000, v2
	s_mov_b32 m0, s26
	v_readfirstlane_b32 s26, v70
	v_add_u32_e32 v70, 0x6000, v2
	s_waitcnt vmcnt(0)
	s_waitcnt vmcnt(0) lgkmcnt(0)
	s_barrier
	global_load_lds_dwordx4 v[68:69], off
	v_lshl_add_u64 v[68:69], v[142:143], 0, s[34:35]
	s_mov_b32 m0, s26
	v_readfirstlane_b32 s26, v70
	v_add_u32_e32 v70, 0x7000, v2
	global_load_lds_dwordx4 v[68:69], off
	v_lshl_add_u64 v[68:69], v[144:145], 0, s[34:35]
	s_mov_b32 m0, s26
	v_readfirstlane_b32 s26, v70
	global_load_lds_dwordx4 v[68:69], off
	v_lshl_add_u64 v[68:69], v[146:147], 0, s[34:35]
	s_mov_b32 m0, s26
	s_and_b32 s25, s25, 0x8000
	global_load_lds_dwordx4 v[68:69], off
	v_or_b32_e32 v68, s25, v175
	v_add_u32_e32 v69, v68, v182
	v_add_u32_e32 v68, v68, v181
	v_or_b32_e32 v72, s25, v176
	v_readfirstlane_b32 s25, v2
	v_add_u32_e32 v158, 0x1000, v2
	ds_read_b128 v[104:107], v69
	ds_read_b128 v[100:103], v69 offset:2048
	ds_read_b128 v[96:99], v69 offset:4096
	ds_read_b128 v[84:87], v69 offset:6144
	ds_read_b128 v[184:187], v68 offset:16384
	ds_read_b128 v[188:191], v68 offset:18432
	ds_read_b128 v[192:195], v68 offset:20480
	ds_read_b128 v[196:199], v68 offset:22528
	v_add_u32_e32 v68, v72, v182
	v_add_u32_e32 v76, v72, v181
	v_lshl_add_u64 v[208:209], v[148:149], 0, s[34:35]
	s_mov_b32 m0, s25
	v_readfirstlane_b32 s25, v158
	v_add_u32_e32 v158, 0x2000, v2
	ds_read_b128 v[200:203], v68
	ds_read_b128 v[204:207], v68 offset:2048
	ds_read_b128 v[92:95], v68 offset:4096
	ds_read_b128 v[68:71], v68 offset:6144
	ds_read_b128 v[88:91], v76 offset:16384
	ds_read_b128 v[80:83], v76 offset:18432
	ds_read_b128 v[72:75], v76 offset:20480
	ds_read_b128 v[76:79], v76 offset:22528
	global_load_lds_dwordx4 v[208:209], off
	v_lshl_add_u64 v[208:209], v[150:151], 0, s[34:35]
	s_mov_b32 m0, s25
	v_readfirstlane_b32 s25, v158
	v_add_u32_e32 v2, 0x3000, v2
	global_load_lds_dwordx4 v[208:209], off
	v_lshl_add_u64 v[208:209], v[152:153], 0, s[34:35]
	s_mov_b32 m0, s25
	v_readfirstlane_b32 s25, v2
	global_load_lds_dwordx4 v[208:209], off
	v_lshl_add_u64 v[208:209], v[154:155], 0, s[34:35]
	s_mov_b32 m0, s25
	s_waitcnt lgkmcnt(0)
	v_mfma_f32_16x16x32_bf16 v[64:67], v[184:187], v[104:107], v[64:67]
	global_load_lds_dwordx4 v[208:209], off
	s_add_u32 s34, s34, 0x80
	v_mfma_f32_16x16x32_bf16 v[60:63], v[188:191], v[104:107], v[60:63]
	s_addc_u32 s35, s35, 0
	s_cmpk_lg_i32 s34, 0x780
	s_mov_b32 s25, s24
	v_mfma_f32_16x16x32_bf16 v[56:59], v[192:195], v[104:107], v[56:59]
	v_mfma_f32_16x16x32_bf16 v[44:47], v[196:199], v[104:107], v[44:47]
	v_mfma_f32_16x16x32_bf16 v[36:39], v[184:187], v[100:103], v[36:39]
	v_mfma_f32_16x16x32_bf16 v[28:31], v[188:191], v[100:103], v[28:31]
	v_mfma_f32_16x16x32_bf16 v[12:15], v[192:195], v[100:103], v[12:15]
	v_mfma_f32_16x16x32_bf16 v[24:27], v[196:199], v[100:103], v[24:27]
	v_mfma_f32_16x16x32_bf16 v[8:11], v[184:187], v[96:99], v[8:11]
	v_mfma_f32_16x16x32_bf16 v[20:23], v[188:191], v[96:99], v[20:23]
	v_mfma_f32_16x16x32_bf16 v[32:35], v[192:195], v[96:99], v[32:35]
	v_mfma_f32_16x16x32_bf16 v[52:55], v[196:199], v[96:99], v[52:55]
	v_mfma_f32_16x16x32_bf16 v[48:51], v[184:187], v[84:87], v[48:51]
	v_mfma_f32_16x16x32_bf16 v[40:43], v[188:191], v[84:87], v[40:43]
	v_mfma_f32_16x16x32_bf16 v[16:19], v[192:195], v[84:87], v[16:19]
	v_mfma_f32_16x16x32_bf16 v[4:7], v[196:199], v[84:87], v[4:7]
	v_mfma_f32_16x16x32_bf16 v[64:67], v[88:91], v[200:203], v[64:67]
	v_mfma_f32_16x16x32_bf16 v[60:63], v[80:83], v[200:203], v[60:63]
	v_mfma_f32_16x16x32_bf16 v[56:59], v[72:75], v[200:203], v[56:59]
	v_mfma_f32_16x16x32_bf16 v[44:47], v[76:79], v[200:203], v[44:47]
	v_mfma_f32_16x16x32_bf16 v[36:39], v[88:91], v[204:207], v[36:39]
	v_mfma_f32_16x16x32_bf16 v[28:31], v[80:83], v[204:207], v[28:31]
	v_mfma_f32_16x16x32_bf16 v[12:15], v[72:75], v[204:207], v[12:15]
	v_mfma_f32_16x16x32_bf16 v[24:27], v[76:79], v[204:207], v[24:27]
	v_mfma_f32_16x16x32_bf16 v[8:11], v[88:91], v[92:95], v[8:11]
	v_mfma_f32_16x16x32_bf16 v[20:23], v[80:83], v[92:95], v[20:23]
	v_mfma_f32_16x16x32_bf16 v[32:35], v[72:75], v[92:95], v[32:35]
	v_mfma_f32_16x16x32_bf16 v[52:55], v[76:79], v[92:95], v[52:55]
	v_mfma_f32_16x16x32_bf16 v[48:51], v[88:91], v[68:71], v[48:51]
	v_mfma_f32_16x16x32_bf16 v[40:43], v[80:83], v[68:71], v[40:43]
	v_mfma_f32_16x16x32_bf16 v[16:19], v[72:75], v[68:71], v[16:19]
	v_mfma_f32_16x16x32_bf16 v[4:7], v[76:79], v[68:71], v[4:7]
	s_cbranch_scc1 .LBB0_649
	v_add_u32_e32 v2, v175, v181
	s_waitcnt vmcnt(0)
	s_waitcnt vmcnt(0) lgkmcnt(0)
	s_barrier
	ds_read_b128 v[68:71], v2 offset:49152
	v_add_u32_e32 v92, v175, v182
	ds_read_b128 v[72:75], v2 offset:51200
	ds_read_b128 v[76:79], v92 offset:32768
	ds_read_b128 v[80:83], v92 offset:34816
	ds_read_b128 v[84:87], v2 offset:53248
	ds_read_b128 v[88:91], v2 offset:55296
	s_waitcnt lgkmcnt(3)
	v_mfma_f32_16x16x32_bf16 v[64:67], v[68:71], v[76:79], v[64:67]
	v_add_u32_e32 v2, v176, v182
	v_add_u32_e32 v104, v176, v181
	s_add_i32 s23, s23, s0
	s_cmpk_lg_i32 s0, 0x200
	s_cbranch_scc1 .Ltail_skip_3
	s_cmpk_lt_i32 s23, 0x1000
	s_cbranch_scc1 .Ltail_skip_3
	s_cmpk_ge_i32 s23, 0x1200
	s_cbranch_scc1 .Ltail_skip_3
	v_readlane_b32 s23, v254, 61
	s_nop 3
	s_addk_i32 s23, 0x1000
; __device__ __forceinline__ unsigned pk2(float lo, float hi) { const f32x2_t v = {lo, hi}; const bf16x2_t b = __builtin_convertvector(v, bf16x2_t); return __builtin_bit_cast(unsigned, b); }
; template <int EPI>
; __device__ __forceinline__ void gemm_tile(const bf16_t* __restrict__ A, const int lda, const bf16_t* __restrict__ Bt, const int ldb,
;                                           const int K, const int m0, const int n0, void* Cout, const int ldc, char* lds, const int tid) {
;     ...
; #pragma unroll
;   for (int m = 0; m < 4; ++m) {
;     const int row = m0 + wr * 64 + m * 16 + fr;
;     if (EPI == EPI_BF16) {
;       bf16_t* C = (bf16_t*)Cout + (size_t)row * ldc + n0 + wc * 64 + fq * 8;
; #pragma unroll
;       for (int pq = 0; pq < 2; ++pq) { uint4 o; o.x = pk2(acc[m][2 * pq][0], acc[m][2 * pq][1]); o.y = pk2(acc[m][2 * pq][2], acc[m][2 * pq][3]);
;         o.z = pk2(acc[m][2 * pq + 1][0], acc[m][2 * pq + 1][1]); o.w = pk2(acc[m][2 * pq + 1][2], acc[m][2 * pq + 1][3]); *(uint4*)(C + pq * 32) = o; }
.Ltail_skip_3:
	v_mfma_f32_16x16x32_bf16 v[60:63], v[72:75], v[76:79], v[60:63]
	s_waitcnt lgkmcnt(1)
	v_mfma_f32_16x16x32_bf16 v[56:59], v[84:87], v[76:79], v[56:59]
	s_waitcnt lgkmcnt(0)
	v_mfma_f32_16x16x32_bf16 v[44:47], v[88:91], v[76:79], v[44:47]
	v_mfma_f32_16x16x32_bf16 v[36:39], v[68:71], v[80:83], v[36:39]
	v_mfma_f32_16x16x32_bf16 v[28:31], v[72:75], v[80:83], v[28:31]
	v_mfma_f32_16x16x32_bf16 v[12:15], v[84:87], v[80:83], v[12:15]
	v_mfma_f32_16x16x32_bf16 v[24:27], v[88:91], v[80:83], v[24:27]
	ds_read_b128 v[76:79], v92 offset:36864
	ds_read_b128 v[80:83], v92 offset:38912
	s_waitcnt lgkmcnt(1)
	v_mfma_f32_16x16x32_bf16 v[8:11], v[68:71], v[76:79], v[8:11]
	v_mfma_f32_16x16x32_bf16 v[20:23], v[72:75], v[76:79], v[20:23]
	v_mfma_f32_16x16x32_bf16 v[32:35], v[84:87], v[76:79], v[32:35]
	v_mfma_f32_16x16x32_bf16 v[52:55], v[88:91], v[76:79], v[52:55]
	s_waitcnt lgkmcnt(0)
	v_mfma_f32_16x16x32_bf16 v[48:51], v[68:71], v[80:83], v[48:51]
	ds_read_b128 v[68:71], v2 offset:32768
	ds_read_b128 v[76:79], v2 offset:34816
	ds_read_b128 v[92:95], v104 offset:49152
	v_mfma_f32_16x16x32_bf16 v[40:43], v[72:75], v[80:83], v[40:43]
	ds_read_b128 v[72:75], v2 offset:36864
	ds_read_b128 v[96:99], v2 offset:38912
	ds_read_b128 v[100:103], v104 offset:51200
	v_or_b32_e32 v2, s3, v131
	v_add_u32_e32 v2, v2, v183
	v_mfma_f32_16x16x32_bf16 v[16:19], v[84:87], v[80:83], v[16:19]
	ds_read_b128 v[84:87], v104 offset:53248
	ds_read_b128 v[104:107], v104 offset:55296
	s_ashr_i32 s3, s2, 31
	v_lshl_add_u64 v[140:141], s[2:3], 1, v[134:135]
	s_waitcnt lgkmcnt(1)
	v_mfma_f32_16x16x32_bf16 v[56:59], v[84:87], v[68:71], v[56:59]
	v_mad_i64_i32 v[142:143], s[2:3], v2, s68, v[140:141]
	s_cmpk_gt_i32 s23, 0x101a
	s_waitcnt lgkmcnt(0)
	v_mfma_f32_16x16x32_bf16 v[44:47], v[104:107], v[68:71], v[44:47]
	s_nop 3
	v_cvt_pk_bf16_f32 v56, v56, v57
	v_cvt_pk_bf16_f32 v57, v58, v59
	v_mfma_f32_16x16x32_bf16 v[12:15], v[84:87], v[76:79], v[12:15]
	v_mfma_f32_16x16x32_bf16 v[24:27], v[104:107], v[76:79], v[24:27]
	v_cvt_pk_bf16_f32 v58, v44, v45
	v_or_b32_e32 v44, 16, v2
	v_mad_i64_i32 v[44:45], s[2:3], v44, s68, v[140:141]
	s_nop 3
	v_cvt_pk_bf16_f32 v12, v12, v13
	v_cvt_pk_bf16_f32 v13, v14, v15
	v_cvt_pk_bf16_f32 v14, v24, v25
	v_cvt_pk_bf16_f32 v15, v26, v27
	v_mfma_f32_16x16x32_bf16 v[8:11], v[92:95], v[72:75], v[8:11]
	global_store_dwordx4 v[44:45], v[12:15], off offset:64
	v_or_b32_e32 v24, 32, v2
	v_mad_i64_i32 v[24:25], s[2:3], v24, s68, v[140:141]
	v_mfma_f32_16x16x32_bf16 v[12:15], v[100:103], v[72:75], v[20:23]
	s_nop 3
	v_cvt_pk_bf16_f32 v8, v8, v9
	v_cvt_pk_bf16_f32 v9, v10, v11
	v_or_b32_e32 v2, 48, v2
	v_mfma_f32_16x16x32_bf16 v[20:23], v[84:87], v[72:75], v[32:35]
	v_cvt_pk_bf16_f32 v59, v46, v47
	v_cvt_pk_bf16_f32 v10, v12, v13
	v_cvt_pk_bf16_f32 v11, v14, v15
	global_store_dwordx4 v[24:25], v[8:11], off
	v_mfma_f32_16x16x32_bf16 v[4:7], v[88:91], v[80:83], v[4:7]
	s_nop 2
	v_cvt_pk_bf16_f32 v12, v20, v21
	v_cvt_pk_bf16_f32 v13, v22, v23
	v_mad_i64_i32 v[20:21], s[2:3], v2, s68, v[140:141]
	v_mfma_f32_16x16x32_bf16 v[8:11], v[104:107], v[72:75], v[52:55]
	global_store_dwordx4 v[142:143], v[56:59], off offset:64
	v_mfma_f32_16x16x32_bf16 v[64:67], v[92:95], v[68:71], v[64:67]
	v_mfma_f32_16x16x32_bf16 v[60:63], v[100:103], v[68:71], v[60:63]
	s_nop 4
	v_cvt_pk_bf16_f32 v14, v8, v9
	v_cvt_pk_bf16_f32 v15, v10, v11
	global_store_dwordx4 v[24:25], v[12:15], off offset:64
	v_mfma_f32_16x16x32_bf16 v[8:11], v[92:95], v[96:99], v[48:51]
	v_cvt_pk_bf16_f32 v64, v64, v65
	v_cvt_pk_bf16_f32 v65, v66, v67
	v_cvt_pk_bf16_f32 v66, v60, v61
	v_mfma_f32_16x16x32_bf16 v[12:15], v[100:103], v[96:99], v[40:43]
	v_cvt_pk_bf16_f32 v67, v62, v63
	s_nop 2
	v_cvt_pk_bf16_f32 v8, v8, v9
	v_cvt_pk_bf16_f32 v9, v10, v11
	v_mfma_f32_16x16x32_bf16 v[36:39], v[92:95], v[76:79], v[36:39]
	global_store_dwordx4 v[142:143], v[64:67], off
	v_cvt_pk_bf16_f32 v10, v12, v13
	v_cvt_pk_bf16_f32 v11, v14, v15
	v_mfma_f32_16x16x32_bf16 v[28:31], v[100:103], v[76:79], v[28:31]
	global_store_dwordx4 v[20:21], v[8:11], off
	s_nop 2
	v_cvt_pk_bf16_f32 v36, v36, v37
	v_cvt_pk_bf16_f32 v37, v38, v39
	v_mfma_f32_16x16x32_bf16 v[12:15], v[84:87], v[96:99], v[16:19]
	v_mfma_f32_16x16x32_bf16 v[4:7], v[104:107], v[96:99], v[4:7]
	v_cvt_pk_bf16_f32 v38, v28, v29
	v_cvt_pk_bf16_f32 v39, v30, v31
	s_nop 4
	v_cvt_pk_bf16_f32 v8, v12, v13
	v_cvt_pk_bf16_f32 v9, v14, v15
	global_store_dwordx4 v[44:45], v[36:39], off
	v_cvt_pk_bf16_f32 v10, v4, v5
	v_cvt_pk_bf16_f32 v11, v6, v7
	global_store_dwordx4 v[20:21], v[8:11], off offset:64
	s_cbranch_scc0 .LBB0_648
